# prologue row conversion (f32 rows -> bf16 + 1/rms) hand-written with three rows (12 loads) in flight per wave, same arithmetic sequence
# speedup vs baseline: 1.0045x; 1.0045x over previous
; __device__ __forceinline__ unsigned cvtpk(float lo, float hi) { f32x2_t v = {lo, hi}; bf16x2_t b = __builtin_convertvector(v, bf16x2_t); return __builtin_bit_cast(unsigned, b); }
; __device__ __forceinline__ void prologue(const Args& A, LAS unsigned char* lds, int wave, int lane) {
;     ...
;     bf16* XA = (bf16*)(ws + WS_XA); float* RS1 = (float*)(ws + WS_RS1);
;     for (int row = gw; row < M1; row += NGW) {
;         const float* src = row < ROW_SAMP ? A.in[0] + (size_t)row * DM : row < ROW_META ? A.in[1] + (size_t)(row - ROW_SAMP) * DM : row < ROW_END ? A.in[6] + (size_t)(row - ROW_META) * DM : nullptr;
;         f32x4 v[4]; float s = 0.f;
; #pragma unroll
;         for (int j = 0; j < 4; ++j) { v[j] = src ? ((const f32x4*)src)[lane + 64 * j] : (f32x4){0.f, 0.f, 0.f, 0.f}; s += (v[j][0] * v[j][0] + v[j][1] * v[j][1]) + (v[j][2] * v[j][2] + v[j][3] * v[j][3]); }
;         s = wave_sum(s);
;         if (lane == 0) RS1[row] = src ? 1.0f / sqrtf(s * (1.0f / DM) + NORM_EPS) : 0.f;
;         u32x2* o = (u32x2*)(XA + (size_t)row * DM) + lane;
; #pragma unroll
;         for (int j = 0; j < 4; ++j) o[64 * j] = (u32x2){cvtpk(v[j][0], v[j][1]), cvtpk(v[j][2], v[j][3])};
;     }
.LBB0_62:
	s_cmpk_gt_i32 s84, 0x42ff
	v_mbcnt_lo_u32_b32 v137, -1, 0
	s_cbranch_scc1 .LBB0_85
	v_mbcnt_hi_u32_b32 v2, -1, v137
	v_and_b32_e32 v1, 64, v2
	v_add_u32_e32 v3, 64, v1
	v_xor_b32_e32 v1, 1, v2
	v_cmp_lt_i32_e32 vcc, v1, v3
	v_xor_b32_e32 v4, 2, v2
	v_mov_b32_e32 v19, 0
	v_cndmask_b32_e32 v1, v2, v1, vcc
	v_cmp_lt_i32_e32 vcc, v4, v3
	v_lshlrev_b32_e32 v18, 3, v136
	s_mov_b64 s[0:1], 0x4400000
	v_cndmask_b32_e32 v4, v2, v4, vcc
	v_lshlrev_b32_e32 v24, 2, v4
	v_xor_b32_e32 v4, 4, v2
	v_cmp_lt_i32_e32 vcc, v4, v3
	s_ashr_i32 s85, s84, 31
	v_readlane_b32 s36, v250, 10
	v_cndmask_b32_e32 v4, v2, v4, vcc
	v_lshlrev_b32_e32 v25, 2, v4
	v_xor_b32_e32 v4, 8, v2
	v_cmp_lt_i32_e32 vcc, v4, v3
	v_readlane_b32 s37, v250, 11
	s_mov_b32 s9, 0
	v_cndmask_b32_e32 v4, v2, v4, vcc
	v_lshlrev_b32_e32 v26, 2, v4
	v_xor_b32_e32 v4, 16, v2
	v_cmp_lt_i32_e32 vcc, v4, v3
	v_lshlrev_b32_e32 v1, 2, v1
	v_cmp_ne_u32_e64 s[2:3], 0, v136
	v_cndmask_b32_e32 v4, v2, v4, vcc
	v_lshlrev_b32_e32 v27, 2, v4
	v_xor_b32_e32 v4, 32, v2
	v_cmp_lt_i32_e32 vcc, v4, v3
	s_mov_b32 s18, 0xf800000
	v_mov_b32_e32 v29, 0x260
	v_cndmask_b32_e32 v2, v2, v4, vcc
	v_lshlrev_b32_e32 v28, 2, v2
	v_lshl_add_u64 v[2:3], s[80:81], 0, v[18:19]
	v_lshl_add_u64 v[20:21], v[2:3], 0, s[0:1]
	s_lshl_b64 s[0:1], s[84:85], 12
	s_add_u32 s10, s36, s0
	s_addc_u32 s11, s37, s1
	s_ashr_i32 s29, s28, 31
	s_lshl_b64 s[12:13], s[28:29], 12
	s_lshl_b64 s[0:1], s[84:85], 2
	s_add_u32 s0, s80, s0
	s_addc_u32 s1, s81, s1
	s_add_u32 s14, s0, 0x1900000
	s_addc_u32 s15, s1, 0
	s_lshl_b64 s[16:17], s[28:29], 2
	v_mov_b32_e32 v18, 0x358637bd
	v_lshlrev_b32_e32 v30, 4, v136
	s_mov_b64 s[20:21], s[84:85]
	v_readlane_b32 s38, v250, 12
	v_readlane_b32 s39, v250, 13
	v_readlane_b32 s40, v250, 14
	v_readlane_b32 s41, v250, 15
	v_readlane_b32 s42, v250, 16
	v_readlane_b32 s43, v250, 17
	v_readlane_b32 s44, v250, 18
	v_readlane_b32 s45, v250, 19
	v_readlane_b32 s46, v250, 20
	v_readlane_b32 s47, v250, 21
	v_readlane_b32 s48, v250, 22
	v_readlane_b32 s49, v250, 23
	v_readlane_b32 s50, v250, 24
	v_readlane_b32 s51, v250, 25
	s_lshl_b32 s16, s28, 1
	s_add_i32 s17, s16, s28
.Lrow_trip:
	s_mov_b32 s24, 0
	s_mov_b32 s25, 0
	s_mov_b32 s8, s20
	s_cmpk_gt_i32 s8, 0x42ff
	s_cbranch_scc1 .Lrow_ld_done
	s_bitset1_b32 s24, 0
	s_cmpk_lt_i32 s8, 0x4000
	s_cbranch_scc0 .Lrow_s1_0
	s_lshl_b64 s[0:1], s[8:9], 12
	s_add_u32 s0, s36, s0
	s_addc_u32 s1, s37, s1
	s_branch .Lrow_ld_0
.Lrow_s1_0:
	s_cmpk_lt_i32 s8, 0x4200
	s_cbranch_scc0 .Lrow_s2_0
	s_add_i32 s4, s8, 0xffffc000
	s_mov_b32 s5, 0
	s_lshl_b64 s[0:1], s[4:5], 12
	s_add_u32 s0, s38, s0
	s_addc_u32 s1, s39, s1
	s_branch .Lrow_ld_0
.Lrow_s2_0:
	s_cmpk_lt_i32 s8, 0x4210
	s_cbranch_scc0 .Lrow_zero_0
	s_add_i32 s4, s8, 0xffffbe00
	s_mov_b32 s5, 0
	s_lshl_b64 s[0:1], s[4:5], 12
	s_add_u32 s0, s48, s0
	s_addc_u32 s1, s49, s1
.Lrow_ld_0:
	s_bitset1_b32 s25, 0
	global_load_dwordx4 v[48:51], v30, s[0:1]
	global_load_dwordx4 v[52:55], v30, s[0:1] offset:1024
	global_load_dwordx4 v[56:59], v30, s[0:1] offset:2048
	global_load_dwordx4 v[60:63], v30, s[0:1] offset:3072
	s_branch .Lrow_next_0
.Lrow_zero_0:
	v_mov_b32_e32 v48, 0
	v_mov_b32_e32 v49, 0
	v_mov_b32_e32 v50, 0
	v_mov_b32_e32 v51, 0
	v_mov_b32_e32 v52, 0
	v_mov_b32_e32 v53, 0
	v_mov_b32_e32 v54, 0
	v_mov_b32_e32 v55, 0
	v_mov_b32_e32 v56, 0
	v_mov_b32_e32 v57, 0
	v_mov_b32_e32 v58, 0
	v_mov_b32_e32 v59, 0
	v_mov_b32_e32 v60, 0
	v_mov_b32_e32 v61, 0
	v_mov_b32_e32 v62, 0
	v_mov_b32_e32 v63, 0
.Lrow_next_0:
	s_add_i32 s8, s20, s28
	s_cmpk_gt_i32 s8, 0x42ff
	s_cbranch_scc1 .Lrow_ld_done
	s_bitset1_b32 s24, 1
	s_cmpk_lt_i32 s8, 0x4000
	s_cbranch_scc0 .Lrow_s1_1
	s_lshl_b64 s[0:1], s[8:9], 12
	s_add_u32 s0, s36, s0
	s_addc_u32 s1, s37, s1
	s_branch .Lrow_ld_1

; __device__ __forceinline__ void prologue(const Args& A, LAS unsigned char* lds, int wave, int lane) {
;     ...
;         const float* src = row < ROW_SAMP ? A.in[0] + (size_t)row * DM : row < ROW_META ? A.in[1] + (size_t)(row - ROW_SAMP) * DM : row < ROW_END ? A.in[6] + (size_t)(row - ROW_META) * DM : nullptr;
;         f32x4 v[4]; float s = 0.f;
; #pragma unroll
;         for (int j = 0; j < 4; ++j) { v[j] = src ? ((const f32x4*)src)[lane + 64 * j] : (f32x4){0.f, 0.f, 0.f, 0.f}; s += (v[j][0] * v[j][0] + v[j][1] * v[j][1]) + (v[j][2] * v[j][2] + v[j][3] * v[j][3]); }
.Lrow_ld_1:
	s_bitset1_b32 s25, 1
	global_load_dwordx4 v[64:67], v30, s[0:1]
	global_load_dwordx4 v[68:71], v30, s[0:1] offset:1024
	global_load_dwordx4 v[72:75], v30, s[0:1] offset:2048
	global_load_dwordx4 v[76:79], v30, s[0:1] offset:3072
	s_branch .Lrow_next_1
.Lrow_zero_1:
	v_mov_b32_e32 v64, 0
	v_mov_b32_e32 v65, 0
	v_mov_b32_e32 v66, 0
	v_mov_b32_e32 v67, 0
	v_mov_b32_e32 v68, 0
	v_mov_b32_e32 v69, 0
	v_mov_b32_e32 v70, 0
	v_mov_b32_e32 v71, 0
	v_mov_b32_e32 v72, 0
	v_mov_b32_e32 v73, 0
	v_mov_b32_e32 v74, 0
	v_mov_b32_e32 v75, 0
	v_mov_b32_e32 v76, 0
	v_mov_b32_e32 v77, 0
	v_mov_b32_e32 v78, 0
	v_mov_b32_e32 v79, 0
.Lrow_next_1:
	s_add_i32 s8, s20, s16
	s_cmpk_gt_i32 s8, 0x42ff
	s_cbranch_scc1 .Lrow_ld_done
	s_bitset1_b32 s24, 2
	s_cmpk_lt_i32 s8, 0x4000
	s_cbranch_scc0 .Lrow_s1_2
	s_lshl_b64 s[0:1], s[8:9], 12
	s_add_u32 s0, s36, s0
	s_addc_u32 s1, s37, s1
	s_branch .Lrow_ld_2

; __device__ __forceinline__ void prologue(const Args& A, LAS unsigned char* lds, int wave, int lane) {
;     ...
;         const float* src = row < ROW_SAMP ? A.in[0] + (size_t)row * DM : row < ROW_META ? A.in[1] + (size_t)(row - ROW_SAMP) * DM : row < ROW_END ? A.in[6] + (size_t)(row - ROW_META) * DM : nullptr;
;         f32x4 v[4]; float s = 0.f;
; #pragma unroll
;         for (int j = 0; j < 4; ++j) { v[j] = src ? ((const f32x4*)src)[lane + 64 * j] : (f32x4){0.f, 0.f, 0.f, 0.f}; s += (v[j][0] * v[j][0] + v[j][1] * v[j][1]) + (v[j][2] * v[j][2] + v[j][3] * v[j][3]); }
;         s = wave_sum(s);
;         if (lane == 0) RS1[row] = src ? 1.0f / sqrtf(s * (1.0f / DM) + NORM_EPS) : 0.f;
.Lrow_ld_2:
	s_bitset1_b32 s25, 2
	global_load_dwordx4 v[2:5], v30, s[0:1]
	global_load_dwordx4 v[6:9], v30, s[0:1] offset:1024
	global_load_dwordx4 v[10:13], v30, s[0:1] offset:2048
	global_load_dwordx4 v[14:17], v30, s[0:1] offset:3072
	s_branch .Lrow_next_2
.Lrow_zero_2:
	v_mov_b32_e32 v2, 0
	v_mov_b32_e32 v3, 0
	v_mov_b32_e32 v4, 0
	v_mov_b32_e32 v5, 0
	v_mov_b32_e32 v6, 0
	v_mov_b32_e32 v7, 0
	v_mov_b32_e32 v8, 0
	v_mov_b32_e32 v9, 0
	v_mov_b32_e32 v10, 0
	v_mov_b32_e32 v11, 0
	v_mov_b32_e32 v12, 0
	v_mov_b32_e32 v13, 0
	v_mov_b32_e32 v14, 0
	v_mov_b32_e32 v15, 0
	v_mov_b32_e32 v16, 0
	v_mov_b32_e32 v17, 0
.Lrow_next_2:
.Lrow_ld_done:
	s_waitcnt vmcnt(0)
	v_mul_f32_e32 v31, v49, v49
	v_mul_f32_e32 v33, v51, v51
	v_fmac_f32_e32 v31, v48, v48
	v_fmac_f32_e32 v33, v50, v50
	v_add_f32_e32 v31, v31, v33
	v_mul_f32_e32 v32, v53, v53
	v_mul_f32_e32 v33, v55, v55
	v_fmac_f32_e32 v32, v52, v52
	v_fmac_f32_e32 v33, v54, v54
	v_add_f32_e32 v32, v32, v33
	v_add_f32_e32 v31, v31, v32
	v_mul_f32_e32 v32, v57, v57
	v_mul_f32_e32 v33, v59, v59
	v_fmac_f32_e32 v32, v56, v56
	v_fmac_f32_e32 v33, v58, v58
	v_add_f32_e32 v32, v32, v33
	v_add_f32_e32 v31, v31, v32
	v_mul_f32_e32 v32, v61, v61
	v_mul_f32_e32 v33, v63, v63
	v_fmac_f32_e32 v32, v60, v60
	v_fmac_f32_e32 v33, v62, v62
	v_add_f32_e32 v32, v32, v33
	v_add_f32_e32 v31, v31, v32
	v_mul_f32_e32 v37, v65, v65
	v_mul_f32_e32 v39, v67, v67
	v_fmac_f32_e32 v37, v64, v64
	v_fmac_f32_e32 v39, v66, v66
	v_add_f32_e32 v37, v37, v39
	v_mul_f32_e32 v38, v69, v69
	v_mul_f32_e32 v39, v71, v71
	v_fmac_f32_e32 v38, v68, v68
	v_fmac_f32_e32 v39, v70, v70
	v_add_f32_e32 v38, v38, v39
	v_add_f32_e32 v37, v37, v38
	v_mul_f32_e32 v38, v73, v73
	v_mul_f32_e32 v39, v75, v75
	v_fmac_f32_e32 v38, v72, v72
	v_fmac_f32_e32 v39, v74, v74
	v_add_f32_e32 v38, v38, v39
	v_add_f32_e32 v37, v37, v38
	v_mul_f32_e32 v38, v77, v77
	v_mul_f32_e32 v39, v79, v79
	v_fmac_f32_e32 v38, v76, v76
	v_fmac_f32_e32 v39, v78, v78
	v_add_f32_e32 v38, v38, v39
	v_add_f32_e32 v37, v37, v38
	v_mul_f32_e32 v43, v3, v3
	v_mul_f32_e32 v45, v5, v5
	v_fmac_f32_e32 v43, v2, v2
	v_fmac_f32_e32 v45, v4, v4
	v_add_f32_e32 v43, v43, v45
	v_mul_f32_e32 v44, v7, v7
	v_mul_f32_e32 v45, v9, v9
	v_fmac_f32_e32 v44, v6, v6
	v_fmac_f32_e32 v45, v8, v8
	v_add_f32_e32 v44, v44, v45
	v_add_f32_e32 v43, v43, v44
	v_mul_f32_e32 v44, v11, v11
	v_mul_f32_e32 v45, v13, v13
	v_fmac_f32_e32 v44, v10, v10
	v_fmac_f32_e32 v45, v12, v12
	v_add_f32_e32 v44, v44, v45
	v_add_f32_e32 v43, v43, v44
	v_mul_f32_e32 v44, v15, v15
	v_mul_f32_e32 v45, v17, v17
	v_fmac_f32_e32 v44, v14, v14
	v_fmac_f32_e32 v45, v16, v16
	v_add_f32_e32 v44, v44, v45
	v_add_f32_e32 v43, v43, v44
	ds_bpermute_b32 v32, v1, v31
	ds_bpermute_b32 v38, v1, v37
	ds_bpermute_b32 v44, v1, v43
	s_waitcnt lgkmcnt(2)
	v_add_f32_e32 v31, v31, v32
	s_waitcnt lgkmcnt(1)
	v_add_f32_e32 v37, v37, v38
	s_waitcnt lgkmcnt(0)
	v_add_f32_e32 v43, v43, v44
	ds_bpermute_b32 v32, v24, v31
	ds_bpermute_b32 v38, v24, v37
	ds_bpermute_b32 v44, v24, v43
	s_waitcnt lgkmcnt(2)
	v_add_f32_e32 v31, v31, v32
	s_waitcnt lgkmcnt(1)
	v_add_f32_e32 v37, v37, v38
	s_waitcnt lgkmcnt(0)
	v_add_f32_e32 v43, v43, v44
	ds_bpermute_b32 v32, v25, v31
	ds_bpermute_b32 v38, v25, v37
	ds_bpermute_b32 v44, v25, v43
	s_waitcnt lgkmcnt(2)
	v_add_f32_e32 v31, v31, v32
	s_waitcnt lgkmcnt(1)
	v_add_f32_e32 v37, v37, v38
	s_waitcnt lgkmcnt(0)
	v_add_f32_e32 v43, v43, v44
	ds_bpermute_b32 v32, v26, v31
	ds_bpermute_b32 v38, v26, v37
	ds_bpermute_b32 v44, v26, v43
	s_waitcnt lgkmcnt(2)
	v_add_f32_e32 v31, v31, v32
	s_waitcnt lgkmcnt(1)
	v_add_f32_e32 v37, v37, v38
	s_waitcnt lgkmcnt(0)
	v_add_f32_e32 v43, v43, v44
	ds_bpermute_b32 v32, v27, v31
	ds_bpermute_b32 v38, v27, v37
	ds_bpermute_b32 v44, v27, v43
	s_waitcnt lgkmcnt(2)
	v_add_f32_e32 v31, v31, v32
	s_waitcnt lgkmcnt(1)
	v_add_f32_e32 v37, v37, v38
	s_waitcnt lgkmcnt(0)
	v_add_f32_e32 v43, v43, v44
	ds_bpermute_b32 v32, v28, v31
	ds_bpermute_b32 v38, v28, v37
	ds_bpermute_b32 v44, v28, v43
	s_waitcnt lgkmcnt(2)
	v_add_f32_e32 v31, v31, v32
	s_waitcnt lgkmcnt(1)
	v_add_f32_e32 v37, v37, v38
	s_waitcnt lgkmcnt(0)
	v_add_f32_e32 v43, v43, v44
	s_bitcmp1_b32 s25, 0
	s_cbranch_scc1 .Lrow_rs_0
	v_mov_b32_e32 v36, 0
	s_branch .Lrow_rsd_0
.Lrow_rs_0:
	v_fmamk_f32 v36, v31, 0x3a800000, v18
	v_mul_f32_e32 v32, 0x4f800000, v36
	v_cmp_gt_f32_e32 vcc, s18, v36
	s_nop 1
	v_cndmask_b32_e32 v36, v36, v32, vcc
	v_sqrt_f32_e32 v32, v36
	s_nop 0
	v_add_u32_e32 v33, -1, v32
	v_fma_f32 v35, -v33, v32, v36
	v_add_u32_e32 v34, 1, v32
	v_cmp_ge_f32_e64 s[0:1], 0, v35
	s_nop 1
	v_cndmask_b32_e64 v33, v32, v33, s[0:1]
	v_fma_f32 v32, -v34, v32, v36
	v_cmp_lt_f32_e64 s[0:1], 0, v32
	s_nop 1
	v_cndmask_b32_e64 v32, v33, v34, s[0:1]
	v_mul_f32_e32 v33, 0x37800000, v32
	v_cndmask_b32_e32 v32, v32, v33, vcc
	v_cmp_class_f32_e32 vcc, v36, v29
	s_nop 1
	v_cndmask_b32_e32 v36, v32, v36, vcc
	v_div_scale_f32 v32, s[0:1], v36, v36, 1.0
	v_rcp_f32_e32 v33, v32
	s_nop 0
	v_fma_f32 v34, -v32, v33, 1.0
	v_fmac_f32_e32 v33, v34, v33
	v_div_scale_f32 v34, vcc, 1.0, v36, 1.0
	v_mul_f32_e32 v35, v34, v33
	v_fma_f32 v31, -v32, v35, v34
	v_fmac_f32_e32 v35, v31, v33
	v_fma_f32 v32, -v32, v35, v34
	v_div_fmas_f32 v32, v32, v33, v35
	v_div_fixup_f32 v36, v32, v36, 1.0
; __device__ __forceinline__ unsigned cvtpk(float lo, float hi) { f32x2_t v = {lo, hi}; bf16x2_t b = __builtin_convertvector(v, bf16x2_t); return __builtin_bit_cast(unsigned, b); }
; __device__ __forceinline__ void prologue(const Args& A, LAS unsigned char* lds, int wave, int lane) {
;     ...
;         if (lane == 0) RS1[row] = src ? 1.0f / sqrtf(s * (1.0f / DM) + NORM_EPS) : 0.f;
;         u32x2* o = (u32x2*)(XA + (size_t)row * DM) + lane;
; #pragma unroll
;         for (int j = 0; j < 4; ++j) o[64 * j] = (u32x2){cvtpk(v[j][0], v[j][1]), cvtpk(v[j][2], v[j][3])};
;     }
.Lrow_rsd_0:
	s_bitcmp1_b32 s25, 1
	s_cbranch_scc1 .Lrow_rs_1
	v_mov_b32_e32 v42, 0
	s_branch .Lrow_rsd_1
.Lrow_rs_1:
	v_fmamk_f32 v42, v37, 0x3a800000, v18
	v_mul_f32_e32 v38, 0x4f800000, v42
	v_cmp_gt_f32_e32 vcc, s18, v42
	s_nop 1
	v_cndmask_b32_e32 v42, v42, v38, vcc
	v_sqrt_f32_e32 v38, v42
	s_nop 0
	v_add_u32_e32 v39, -1, v38
	v_fma_f32 v41, -v39, v38, v42
	v_add_u32_e32 v40, 1, v38
	v_cmp_ge_f32_e64 s[0:1], 0, v41
	s_nop 1
	v_cndmask_b32_e64 v39, v38, v39, s[0:1]
	v_fma_f32 v38, -v40, v38, v42
	v_cmp_lt_f32_e64 s[0:1], 0, v38
	s_nop 1
	v_cndmask_b32_e64 v38, v39, v40, s[0:1]
	v_mul_f32_e32 v39, 0x37800000, v38
	v_cndmask_b32_e32 v38, v38, v39, vcc
	v_cmp_class_f32_e32 vcc, v42, v29
	s_nop 1
	v_cndmask_b32_e32 v42, v38, v42, vcc
	v_div_scale_f32 v38, s[0:1], v42, v42, 1.0
	v_rcp_f32_e32 v39, v38
	s_nop 0
	v_fma_f32 v40, -v38, v39, 1.0
	v_fmac_f32_e32 v39, v40, v39
	v_div_scale_f32 v40, vcc, 1.0, v42, 1.0
	v_mul_f32_e32 v41, v40, v39
	v_fma_f32 v37, -v38, v41, v40
	v_fmac_f32_e32 v41, v37, v39
	v_fma_f32 v38, -v38, v41, v40
	v_div_fmas_f32 v38, v38, v39, v41
	v_div_fixup_f32 v42, v38, v42, 1.0
.Lrow_rsd_1:
	s_bitcmp1_b32 s25, 2
	s_cbranch_scc1 .Lrow_rs_2
	v_mov_b32_e32 v81, 0
	s_branch .Lrow_rsd_2
.Lrow_rs_2:
	v_fmamk_f32 v81, v43, 0x3a800000, v18
	v_mul_f32_e32 v44, 0x4f800000, v81
	v_cmp_gt_f32_e32 vcc, s18, v81
	s_nop 1
	v_cndmask_b32_e32 v81, v81, v44, vcc
	v_sqrt_f32_e32 v44, v81
	s_nop 0
	v_add_u32_e32 v45, -1, v44
	v_fma_f32 v80, -v45, v44, v81
	v_add_u32_e32 v46, 1, v44
	v_cmp_ge_f32_e64 s[0:1], 0, v80
	s_nop 1
	v_cndmask_b32_e64 v45, v44, v45, s[0:1]
	v_fma_f32 v44, -v46, v44, v81
	v_cmp_lt_f32_e64 s[0:1], 0, v44
	s_nop 1
	v_cndmask_b32_e64 v44, v45, v46, s[0:1]
	v_mul_f32_e32 v45, 0x37800000, v44
	v_cndmask_b32_e32 v44, v44, v45, vcc
	v_cmp_class_f32_e32 vcc, v81, v29
	s_nop 1
	v_cndmask_b32_e32 v81, v44, v81, vcc
	v_div_scale_f32 v44, s[0:1], v81, v81, 1.0
	v_rcp_f32_e32 v45, v44
	s_nop 0
	v_fma_f32 v46, -v44, v45, 1.0
	v_fmac_f32_e32 v45, v46, v45
	v_div_scale_f32 v46, vcc, 1.0, v81, 1.0
	v_mul_f32_e32 v80, v46, v45
	v_fma_f32 v43, -v44, v80, v46
	v_fmac_f32_e32 v80, v43, v45
	v_fma_f32 v44, -v44, v80, v46
	v_div_fmas_f32 v44, v44, v45, v80
	v_div_fixup_f32 v81, v44, v81, 1.0
.Lrow_rsd_2:
	s_bitcmp1_b32 s24, 0
	s_cbranch_scc0 .Lrow_st_done
	s_mov_b32 s8, s20
	s_lshl_b64 s[0:1], s[8:9], 11
	v_lshl_add_u64 v[22:23], v[20:21], 0, s[0:1]
	v_cvt_pk_bf16_f32 v48, v48, v49
	v_cvt_pk_bf16_f32 v49, v50, v51
	global_store_dwordx2 v[22:23], v[48:49], off
	v_cvt_pk_bf16_f32 v52, v52, v53
	v_cvt_pk_bf16_f32 v53, v54, v55
	global_store_dwordx2 v[22:23], v[52:53], off offset:512
	v_cvt_pk_bf16_f32 v56, v56, v57
	v_cvt_pk_bf16_f32 v57, v58, v59
	global_store_dwordx2 v[22:23], v[56:57], off offset:1024
	v_cvt_pk_bf16_f32 v60, v60, v61
	v_cvt_pk_bf16_f32 v61, v62, v63
	global_store_dwordx2 v[22:23], v[60:61], off offset:1536
	s_lshl_b64 s[0:1], s[8:9], 2
	s_add_u32 s0, s80, s0
	s_addc_u32 s1, s81, s1
	s_add_u32 s0, s0, 0x1900000
	s_addc_u32 s1, s1, 0
	s_mov_b64 s[4:5], exec
	s_mov_b64 exec, 1
	global_store_dword v19, v36, s[0:1]
	s_mov_b64 exec, s[4:5]
	s_bitcmp1_b32 s24, 1
	s_cbranch_scc0 .Lrow_st_done
	s_add_i32 s8, s20, s28
	s_lshl_b64 s[0:1], s[8:9], 11
	v_lshl_add_u64 v[22:23], v[20:21], 0, s[0:1]
	v_cvt_pk_bf16_f32 v64, v64, v65
	v_cvt_pk_bf16_f32 v65, v66, v67
	global_store_dwordx2 v[22:23], v[64:65], off
	v_cvt_pk_bf16_f32 v68, v68, v69
	v_cvt_pk_bf16_f32 v69, v70, v71
	global_store_dwordx2 v[22:23], v[68:69], off offset:512
	v_cvt_pk_bf16_f32 v72, v72, v73
	v_cvt_pk_bf16_f32 v73, v74, v75
	global_store_dwordx2 v[22:23], v[72:73], off offset:1024
	v_cvt_pk_bf16_f32 v76, v76, v77
	v_cvt_pk_bf16_f32 v77, v78, v79
	global_store_dwordx2 v[22:23], v[76:77], off offset:1536
	s_lshl_b64 s[0:1], s[8:9], 2
	s_add_u32 s0, s80, s0
	s_addc_u32 s1, s81, s1
	s_add_u32 s0, s0, 0x1900000
	s_addc_u32 s1, s1, 0
	s_mov_b64 s[4:5], exec
	s_mov_b64 exec, 1
	global_store_dword v19, v42, s[0:1]
	s_mov_b64 exec, s[4:5]
	s_bitcmp1_b32 s24, 2
	s_cbranch_scc0 .Lrow_st_done
	s_add_i32 s8, s20, s16
	s_lshl_b64 s[0:1], s[8:9], 11
	v_lshl_add_u64 v[22:23], v[20:21], 0, s[0:1]
	v_cvt_pk_bf16_f32 v2, v2, v3
	v_cvt_pk_bf16_f32 v3, v4, v5
	global_store_dwordx2 v[22:23], v[2:3], off
	v_cvt_pk_bf16_f32 v6, v6, v7
	v_cvt_pk_bf16_f32 v7, v8, v9
	global_store_dwordx2 v[22:23], v[6:7], off offset:512
	v_cvt_pk_bf16_f32 v10, v10, v11
	v_cvt_pk_bf16_f32 v11, v12, v13
	global_store_dwordx2 v[22:23], v[10:11], off offset:1024
	v_cvt_pk_bf16_f32 v14, v14, v15
	v_cvt_pk_bf16_f32 v15, v16, v17
	global_store_dwordx2 v[22:23], v[14:15], off offset:1536
	s_lshl_b64 s[0:1], s[8:9], 2
	s_add_u32 s0, s80, s0
	s_addc_u32 s1, s81, s1
	s_add_u32 s0, s0, 0x1900000
	s_addc_u32 s1, s1, 0
	s_mov_b64 s[4:5], exec
	s_mov_b64 exec, 1
	global_store_dword v19, v81, s[0:1]
	s_mov_b64 exec, s[4:5]
.Lrow_st_done:
	s_add_i32 s20, s20, s17
	s_cmpk_gt_i32 s20, 0x42ff
	s_cbranch_scc0 .Lrow_trip
